# retention core: next-chunk q/k row loads issued inside stage A as each register group dies (saddr form, scalar chunk bases, per-unit lane offsets), end-of-stage prefetch block with 12 64-bit VALU ops
# speedup vs baseline: 1.0087x; 1.0087x over previous
; #define LAS __attribute__((address_space(3)))
; template <int DK, int DVS, bool RET> ...
;     ...
;     unsigned aQD = (unsigned)(uintptr_t)(LAS unsigned char*)lds, aKD = aQD + 64 * LK * 2, aSTB = aKD + 64 * LK * 2, aVI = aSTB + DVS * LK * 2,
;              aAT = aVI + 64 * LV * 2, aEL = aAT + 64 * LS * 2, aTOT = aEL + DK * 4;
;     asm volatile("" : "+s"(aQD), "+s"(aVI), "+s"(aAT), "+s"(aEL), "+s"(aTOT), "+s"(aKD), "+s"(aSTB));
;     LAS bf16_t* QD = (LAS bf16_t*)(uintptr_t)aQD; LAS bf16_t* VI = (LAS bf16_t*)(uintptr_t)aVI; LAS bf16_t* AT = (LAS bf16_t*)(uintptr_t)aAT;
;     LAS float* EL = (LAS float*)(uintptr_t)aEL; LAS float* TOT = (LAS float*)(uintptr_t)aTOT;
;     LAS bf16_t* KD = (LAS bf16_t*)(uintptr_t)aKD; LAS bf16_t* STB = (LAS bf16_t*)(uintptr_t)aSTB;
;     static_assert(2 * 64 * LK * 2 + DVS * LK * 2 + 64 * LV * 2 + 64 * LS * 2 + DK * 4 + 2048 <= 159744, "GLA LDS map");
;     const int wid = tid >> 6, lane = tid & 63, l16 = lane & 15, quad = lane >> 4;
;     const int tr = wid >> 1, tv = wid / WPV, kt0 = (wid % WPV) * TPW;
;     const int vtr = (int)aVI + (8 * quad + (l16 >> 2)) * (LV * 2) + 8 * (lane & 3);
;     const int ktr = (int)aKD + (8 * quad + (l16 >> 2)) * (LK * 2) + 8 * (lane & 3);
; __global__ void __launch_bounds__(512) mk_fwd(Params P) {
;     ...
;                 const int slice = L & 7, dir = (L >> 3) & 1, hh = (L >> 4) & 3, bq = L >> 6;
;                 const float lg = __logf(1.f - exp2f(-P.in[16][dir * 4 + hh]));
;                 gla_unit<256, 64, true>(lds, bq, hh, dir, slice, Qb, Kb, Vb, nullptr, dir ? OB : OF, lg, 2048, hh * 512 + slice * 64, tid);
.LBB0_69:
	s_bfe_u32 s28, s3, 0x10003
	s_bfe_u32 s24, s3, 0x20004
	s_lshl_b32 s22, s24, 2
	s_lshl_b32 s23, s28, 4
	s_or_b32 s22, s23, s22
	v_mov_b32_e32 v0, s22
	v_readlane_b32 s22, v254, 25
	v_readlane_b32 s23, v254, 26
	s_load_dwordx2 s[22:23], s[22:23], 0x80
	v_readlane_b32 s46, v254, 9
	v_readlane_b32 s29, v254, 4
	s_mov_b32 s30, s37
	v_readlane_b32 s41, v254, 6
	s_waitcnt lgkmcnt(0)
	global_load_dword v1, v0, s[22:23]
	s_ashr_i32 s22, s3, 6
	v_readlane_b32 s23, v254, 7
	v_readlane_b32 s45, v254, 8
	v_readlane_b32 s40, v254, 5
	s_mul_hi_i32 s43, s22, 0x1100
	s_mul_i32 s44, s22, 0x1100
	s_mov_b32 s22, 0x42fc0000
	s_bfe_i32 s25, s3, 0x10003
	v_add_u32_e32 v37, s29, v116
	v_add3_u32 v172, s29, v120, v78
	v_lshlrev_b32_e32 v36, 1, v69
	v_mov_b32_e32 v3, s43
	v_add_u32_e32 v38, s30, v36
	v_add_u32_e32 v40, s30, v170
	v_lshlrev_b64 v[86:87], 1, v[70:71]
	v_lshlrev_b64 v[88:89], 1, v[72:73]
	v_lshlrev_b64 v[90:91], 1, v[74:75]
	v_lshlrev_b64 v[92:93], 1, v[76:77]
	v_add_u32_e32 v41, s45, v170
	v_lshlrev_b32_e32 v49, 1, v70
	s_mov_b32 s31, s37
	v_add_u32_e32 v178, v40, v49
	v_add_u32_e32 v179, v41, v49
	v_lshlrev_b32_e32 v49, 1, v72
	v_lshlrev_b32_e32 v144, 1, v68
	v_add_u32_e32 v180, v40, v49
	v_add_u32_e32 v181, v41, v49
	v_lshlrev_b32_e32 v49, 1, v74
	v_add_u32_e32 v39, s46, v144
	v_add_u32_e32 v182, v40, v49
	v_add_u32_e32 v183, v41, v49
	v_lshlrev_b32_e32 v49, 1, v76
	v_mov_b32_e32 v0, 0
	v_add3_u32 v174, s45, v123, v36
	v_add_u32_e32 v175, s46, v36
	v_add3_u32 v176, s40, v125, v36
	v_lshl_add_u32 v36, v68, 2, s41
	v_add_u32_e32 v42, v39, v129
	v_add_u32_e32 v43, v39, v131
	v_add_u32_e32 v44, v39, v132
	v_add_u32_e32 v45, v39, v133
	v_add_u32_e32 v46, v39, v134
	v_add_u32_e32 v47, v39, v135
	v_add_u32_e32 v48, v39, v136
	v_add_u32_e32 v39, v39, v137
	v_add_u32_e32 v184, v40, v49
	v_lshlrev_b32_e32 v40, 1, v122
	v_mov_b32_e32 v83, v145
	v_mov_b32_e32 v85, v145
	s_mov_b32 s42, 0
	v_mov_b32_e32 v95, s43
	v_lshl_add_u32 v171, v118, 2, s41
	v_add_u32_e32 v177, v37, v128
	v_add_u32_e32 v185, v41, v49
	v_add3_u32 v199, s40, v138, v40
	v_add3_u32 v200, s40, v140, v40
	v_add3_u32 v201, s40, v142, v40
	v_add3_u32 v202, s40, v147, v40
	v_add_u32_e32 v203, v37, v151
	v_add_u32_e32 v210, v42, v130
	v_add_u32_e32 v211, v43, v130
	v_add_u32_e32 v212, v44, v130
	v_add_u32_e32 v213, v45, v130
	v_add_u32_e32 v214, v46, v130
	v_add_u32_e32 v215, v47, v130
	v_add_u32_e32 v216, v48, v130
	v_add_u32_e32 v217, v39, v130
	v_add_u32_e32 v218, v38, v121
	v_add_u32_e32 v219, v175, v155
	v_add_u32_e32 v220, v36, v162
	v_add_u32_e32 v221, v36, v163
	v_add_u32_e32 v222, v36, v164
	v_add_u32_e32 v223, v36, v165
	v_add_u32_e32 v224, v36, v166
	v_add_u32_e32 v225, v36, v167
	v_add_u32_e32 v226, v36, v168
	v_add_u32_e32 v227, v36, v169
	v_mov_b32_e32 v36, v0
	s_waitcnt vmcnt(0)
; #define GAS __attribute__((address_space(1)))
; template <int DK, int DVS, bool RET> ...
;     ...
;     bf16x8 qv[NQV], kv[NQV]; float lc[NLC]; bf16_t qr[NLC]; vvec_t vraw;
;     const int kx = tid % DK, pg = tid / DK;
;     const GAS bf16_t* Qg = (const GAS bf16_t*)Q; const GAS bf16_t* Kg = (const GAS bf16_t*)Kp; const GAS float* LFg = (const GAS float*)LF; const GAS bf16_t* Vg = (const GAS bf16_t*)V;
;     ...
;     GLA_LOAD(0);
; __global__ void __launch_bounds__(512) mk_fwd(Params P) {
;     ...
;                 const float lg = __logf(1.f - exp2f(-P.in[16][dir * 4 + hh]));
;                 gla_unit<256, 64, true>(lds, bq, hh, dir, slice, Qb, Kb, Vb, nullptr, dir ? OB : OF, lg, 2048, hh * 512 + slice * 64, tid);
	v_cmp_lt_f32_e64 s[22:23], s22, v1
	v_mov_b32_e32 v38, v0
	v_mov_b32_e32 v39, v0
	v_cndmask_b32_e64 v2, 0, v195, s[22:23]
	v_sub_f32_e32 v1, v2, v1
	v_exp_f32_e32 v1, v1
	s_and_b64 s[22:23], s[22:23], exec
	s_cselect_b32 s22, 0xffffffc0, 0
	v_xor_b32_e32 v2, 63, v148
	v_ldexp_f32 v1, v1, s22
	v_sub_f32_e32 v1, 1.0, v1
	v_cmp_gt_f32_e64 s[22:23], s53, v1
	v_mov_b32_e32 v44, v0
	v_mov_b32_e32 v45, v0
	v_cndmask_b32_e64 v6, 0, v196, s[22:23]
	s_and_b64 s[22:23], s[22:23], exec
	s_cselect_b32 s22, 32, 0
	s_cmp_eq_u32 s28, 0
	v_ldexp_f32 v1, v1, s22
	s_cselect_b64 s[22:23], -1, 0
	v_log_f32_e32 v1, v1
	s_and_b64 s[28:29], s[22:23], exec
	s_cselect_b32 s28, s47, 0x1ad69000
	s_add_u32 s47, s0, s28
	v_cndmask_b32_e64 v2, v2, v148, s[22:23]
	s_addc_u32 s48, s1, 0
	s_and_b32 s25, s25, 0xc0
	s_lshl_b32 s28, s3, 7
	v_or_b32_e32 v94, s44, v2
	v_mul_f32_e32 v4, 0x3f317217, v1
	v_or_b32_e32 v2, s25, v2
	s_and_b32 s25, s28, 0x380
	s_mov_b32 s28, 0x3f317217
	s_lshl_b32 s36, s24, 9
	s_lshl_b32 s24, s24, 10
	v_fma_f32 v7, v1, s28, -v4
	v_or_b32_e32 v2, s44, v2
	s_or_b32 s30, s24, s25
	v_fmac_f32_e32 v7, 0x3377d1cf, v1
	v_lshlrev_b64 v[2:3], 11, v[2:3]
	s_mov_b32 s24, 0x7f800000
	v_fmac_f32_e32 v7, 0x3f317217, v1
	v_lshl_add_u64 v[4:5], s[90:91], 0, v[2:3]
	v_lshl_add_u64 v[2:3], s[26:27], 0, v[2:3]
	v_cmp_lt_f32_e64 s[24:25], |v1|, s24
	v_lshl_add_u64 v[4:5], v[4:5], 0, s[36:37]
	v_lshl_add_u64 v[2:3], v[2:3], 0, s[36:37]
	v_cndmask_b32_e64 v1, v1, v7, s[24:25]
	v_sub_f32_e32 v1, v1, v6
	v_lshl_add_u64 v[6:7], v[4:5], 0, v[86:87]
	v_lshl_add_u64 v[8:9], v[2:3], 0, v[86:87]
	v_lshl_add_u64 v[12:13], v[4:5], 0, v[88:89]
	v_lshl_add_u64 v[16:17], v[2:3], 0, v[88:89]
	v_lshl_add_u64 v[20:21], v[4:5], 0, v[90:91]
	v_lshl_add_u64 v[24:25], v[2:3], 0, v[90:91]
	v_lshl_add_u64 v[28:29], v[4:5], 0, v[92:93]
	v_lshl_add_u64 v[2:3], v[2:3], 0, v[92:93]
	global_load_dwordx4 v[4:7], v[6:7], off
	s_nop 0
	global_load_dwordx4 v[8:11], v[8:9], off
	s_nop 0
	global_load_dwordx4 v[12:15], v[12:13], off
	s_nop 0
	global_load_dwordx4 v[16:19], v[16:17], off
	s_nop 0
	global_load_dwordx4 v[20:23], v[20:21], off
	s_nop 0
	global_load_dwordx4 v[24:27], v[24:25], off
	s_nop 0
	global_load_dwordx4 v[28:31], v[28:29], off
	s_nop 0
	global_load_dwordx4 v[32:35], v[2:3], off
	s_add_u32 s28, s90, s36
	s_addc_u32 s29, s91, 0
	v_mul_f32_e32 v2, 0x42800000, v1
	v_mul_f32_e32 v1, v1, v79
	s_add_u32 s24, s26, s36
	v_mul_f32_e32 v3, 0x3fb8aa3b, v1
	v_mul_f32_e32 v1, 0xbfb8aa3b, v1
	v_mul_f32_e32 v2, 0x3fb8aa3b, v2
	v_exp_f32_e32 v100, v3
	v_exp_f32_e32 v102, v1
	s_addc_u32 s25, s27, 0
	v_lshl_add_u64 v[98:99], v[80:81], 0, s[30:31]
	v_exp_f32_e32 v173, v2
	s_add_u32 s30, s47, s30
	s_addc_u32 s31, s48, 0
	v_cndmask_b32_e64 v96, v119, v117, s[22:23]
	v_lshl_add_u64 v[2:3], s[30:31], 0, v[144:145]
	v_add_u32_e32 v1, s45, v127
	v_cndmask_b32_e64 v104, v150, v124, s[22:23]
	v_cndmask_b32_e64 v108, v152, v139, s[22:23]
	v_cndmask_b32_e64 v110, v153, v141, s[22:23]
	v_cndmask_b32_e64 v112, v154, v143, s[22:23]
	v_ashrrev_i32_e32 v97, 31, v96
	v_add_u32_e32 v144, v37, v126
	v_ashrrev_i32_e32 v105, 31, v104
	v_lshl_add_u64 v[106:107], v[2:3], 0, v[82:83]
	v_ashrrev_i32_e32 v109, 31, v108
	v_ashrrev_i32_e32 v111, 31, v110
	v_ashrrev_i32_e32 v113, 31, v112
	v_lshl_add_u64 v[114:115], v[2:3], 0, v[84:85]
	v_add_u32_e32 v83, v1, v129
	v_add_u32_e32 v85, v1, v131
	v_add_u32_e32 v204, v1, v156
	v_add_u32_e32 v205, v1, v157
	v_add_u32_e32 v206, v1, v158
	v_add_u32_e32 v207, v1, v159
	v_add_u32_e32 v208, v1, v160
	v_add_u32_e32 v209, v1, v161
	v_mov_b32_e32 v103, v102
	v_mov_b32_e32 v101, v100
	s_mov_b32 s45, 0
	v_mov_b32_e32 v1, v0
	v_mov_b32_e32 v2, v0
	v_mov_b32_e32 v3, v0
	v_mov_b32_e32 v37, v0
	v_mov_b32_e32 v46, v0
	v_mov_b32_e32 v47, v0
	v_mov_b32_e32 v40, v0
	v_mov_b32_e32 v41, v0
	v_mov_b32_e32 v42, v0
	v_mov_b32_e32 v43, v0
	v_mov_b32_e32 v52, v0
	v_mov_b32_e32 v53, v0
	v_mov_b32_e32 v54, v0
	v_mov_b32_e32 v55, v0
	v_mov_b32_e32 v48, v0
	v_mov_b32_e32 v49, v0
	v_mov_b32_e32 v50, v0
	v_mov_b32_e32 v51, v0
	v_mov_b32_e32 v60, v0
	v_mov_b32_e32 v61, v0
	v_mov_b32_e32 v62, v0
	v_mov_b32_e32 v63, v0
	v_mov_b32_e32 v56, v0
	v_mov_b32_e32 v57, v0
	v_mov_b32_e32 v58, v0
	v_mov_b32_e32 v59, v0
	v_subrev_u32_e32 v95, s44, v94
	v_lshl_add_u32 v86, v95, 11, v86
	v_lshl_add_u32 v88, v95, 11, v88
	v_lshl_add_u32 v90, v95, 11, v90
	v_lshl_add_u32 v92, v95, 11, v92
	s_branch .LBB0_71

; #define LAS __attribute__((address_space(3)))
; #define GAS __attribute__((address_space(1)))
; __device__ __forceinline__ bf16_t f2bf(float x) { return (bf16_t)(cvt_pk_bf16(x, x) & 0xffffu); }
; __device__ __forceinline__ float bf2f(bf16_t v) { return __uint_as_float((unsigned)v << 16); }
; __device__ __forceinline__ u32x4 pack8(const float* v) { u32x4 w; w.x = cvt_pk_bf16(v[0], v[1]); w.y = cvt_pk_bf16(v[2], v[3]); w.z = cvt_pk_bf16(v[4], v[5]); w.w = cvt_pk_bf16(v[6], v[7]); return w; }
; #define GLA_BAR() do { asm volatile("s_waitcnt lgkmcnt(0)" ::: "memory"); __builtin_amdgcn_s_barrier(); asm volatile("" ::: "memory"); } while (0)
; template <int DK, int DVS, bool RET> ...
;     ...
;     for (int step = 0; step < 68; ++step) {
;         const int cidx = dir ? (step < 4 ? 3 - step : 71 - step) : step;
;         const long R0 = (long)b * TB + cidx * 64;
;         GLA_BAR();
;         {
; #pragma unroll
;             for (int t = 0; t < TPW; ++t)
; #pragma unroll
;                 for (int j = 0; j < 4; ++j) STB[(tv * 16 + quad * 4 + j) * LK + (kt0 + t) * 16 + l16] = f2bf(st[t][j]);
;             { const int p = tid >> 3, vg = tid & 7; const long row = R0 + (dir ? 63 - p : p); vraw = *(const GAS vvec_t*)(Vg + row * ldv + vcol0 + vg * VPT); }
;             float bl;
;             if constexpr (RET) {
;                 static_assert(!RET || DK == 256, "retention prep: 64 x 256 = 2048 eight-wide items, four per thread");
;                 bl = 64.f * lg;
; #pragma unroll
;                 for (int j = 0; j < 4; ++j) { const int it = tid + 512 * j, p = it & 63, k0 = (it >> 6) * 8; const float bb = (float)(p + 1) * lg;
;                     const float eq = __expf(bb), ek = __expf(-bb); float a[8], c[8];
; #pragma unroll
;                     for (int e = 0; e < 8; ++e) { a[e] = bf2f((bf16_t)qv[j][e]) * eq; c[e] = bf2f((bf16_t)kv[j][e]) * ek; }
;                     *(LAS u32x4*)(QD + p * LK + k0) = pack8(a); *(LAS u32x4*)(KD + p * LK + k0) = pack8(c); }
.LBB0_71:
	v_cvt_pk_bf16_f32 v64, v56, s0
	s_cmp_gt_u32 s45, 3
	s_cselect_b32 s30, 0x47, 3
	s_add_i32 s36, s30, s42
	s_and_b64 s[30:31], s[22:23], exec
	s_cselect_b32 s30, s45, s36
	s_lshl_b32 s30, s30, 6
	s_ashr_i32 s31, s30, 31
	s_add_u32 s30, s44, s30
	s_addc_u32 s31, s43, s31
	v_lshl_add_u64 v[214:215], s[30:31], 0, v[96:97]
	v_lshlrev_b64 v[214:215], 12, v[214:215]
	v_lshl_add_u64 v[214:215], v[98:99], 0, v[214:215]
	global_load_dwordx4 v[212:215], v[214:215], off
	s_add_i32 s39, s45, 1
	s_min_i32 s39, s39, 0x43
	s_cmp_gt_u32 s39, 3
	s_cselect_b32 s38, 0x47, 3
	s_sub_i32 s38, s38, s39
	s_and_b64 s[54:55], s[22:23], exec
	s_cselect_b32 s38, s39, s38
	s_lshl_b32 s38, s38, 6
	s_add_u32 s38, s44, s38
	s_addc_u32 s39, s43, 0
	s_lshl_b64 s[38:39], s[38:39], 11
	s_add_u32 s54, s24, s38
	s_addc_u32 s55, s25, s39
	s_add_u32 s38, s28, s38
	s_addc_u32 s39, s29, s39
	s_waitcnt lgkmcnt(0)
	s_barrier
	ds_write_b16 v210, v64
	v_cvt_pk_bf16_f32 v64, v57, s0
	ds_write_b16 v210, v64 offset:528
	v_cvt_pk_bf16_f32 v64, v58, s0
	ds_write_b16 v210, v64 offset:1056
	v_cvt_pk_bf16_f32 v64, v59, s0
	ds_write_b16 v210, v64 offset:1584
	v_cvt_pk_bf16_f32 v64, v60, s0
	ds_write_b16 v210, v64 offset:32
	v_cvt_pk_bf16_f32 v64, v61, s0
	ds_write_b16 v210, v64 offset:560
	v_cvt_pk_bf16_f32 v64, v62, s0
	ds_write_b16 v210, v64 offset:1088
	v_cvt_pk_bf16_f32 v64, v63, s0
	ds_write_b16 v210, v64 offset:1616
	v_cvt_pk_bf16_f32 v64, v48, s0
	ds_write_b16 v210, v64 offset:64
	v_cvt_pk_bf16_f32 v64, v49, s0
	ds_write_b16 v210, v64 offset:592
	v_cvt_pk_bf16_f32 v64, v50, s0
	ds_write_b16 v210, v64 offset:1120
	v_cvt_pk_bf16_f32 v64, v51, s0
	ds_write_b16 v210, v64 offset:1648
	v_cvt_pk_bf16_f32 v64, v52, s0
	ds_write_b16 v210, v64 offset:96
	v_cvt_pk_bf16_f32 v64, v53, s0
	ds_write_b16 v210, v64 offset:624
	v_cvt_pk_bf16_f32 v64, v54, s0
	ds_write_b16 v210, v64 offset:1152
	v_cvt_pk_bf16_f32 v64, v55, s0
	ds_write_b16 v210, v64 offset:1680
	v_cvt_pk_bf16_f32 v64, v40, s0
	ds_write_b16 v210, v64 offset:128
	v_cvt_pk_bf16_f32 v64, v41, s0
	ds_write_b16 v210, v64 offset:656
	v_cvt_pk_bf16_f32 v64, v42, s0
	ds_write_b16 v210, v64 offset:1184
	v_cvt_pk_bf16_f32 v64, v43, s0
	ds_write_b16 v210, v64 offset:1712
	v_cvt_pk_bf16_f32 v64, v44, s0
	ds_write_b16 v210, v64 offset:160
	v_cvt_pk_bf16_f32 v64, v45, s0
	ds_write_b16 v210, v64 offset:688
	v_cvt_pk_bf16_f32 v64, v46, s0
	s_cmp_gt_u32 s45, 3
	ds_write_b16 v210, v64 offset:1216
	v_cvt_pk_bf16_f32 v64, v47, s0
	s_cselect_b32 s30, 0x47, 3
	ds_write_b16 v210, v64 offset:1744
	v_cvt_pk_bf16_f32 v64, v36, s0
	s_add_i32 s36, s30, s42
	ds_write_b16 v210, v64 offset:192
	v_cvt_pk_bf16_f32 v64, v37, s0
	s_and_b64 s[30:31], s[22:23], exec
	ds_write_b16 v210, v64 offset:720
	v_cvt_pk_bf16_f32 v64, v38, s0
	s_cselect_b32 s30, s45, s36
	ds_write_b16 v210, v64 offset:1248
	v_cvt_pk_bf16_f32 v64, v39, s0
	s_lshl_b32 s30, s30, 6
	ds_write_b16 v210, v64 offset:1776
	v_cvt_pk_bf16_f32 v64, v0, s0
	s_ashr_i32 s31, s30, 31
	ds_write_b16 v210, v64 offset:224
	v_cvt_pk_bf16_f32 v64, v1, s0
	ds_write_b16 v210, v64 offset:752
	v_cvt_pk_bf16_f32 v64, v2, s0
	s_add_u32 s30, s44, s30
	ds_write_b16 v210, v64 offset:1280
	v_cvt_pk_bf16_f32 v64, v3, s0
	s_addc_u32 s31, s43, s31
	ds_write_b16 v210, v64 offset:1808
	s_waitcnt vmcnt(7)
	v_and_b32_e32 v231, 0xffff0000, v8
	v_lshlrev_b32_e32 v230, 16, v8
	v_and_b32_e32 v229, 0xffff0000, v4
	v_lshlrev_b32_e32 v228, 16, v4
	v_pk_mul_f32 v[232:233], v[102:103], v[230:231]
	v_and_b32_e32 v231, 0xffff0000, v5
	v_lshlrev_b32_e32 v230, 16, v5
	v_and_b32_e32 v237, 0xffff0000, v6
	v_lshlrev_b32_e32 v236, 16, v6
	v_and_b32_e32 v241, 0xffff0000, v7
	v_lshlrev_b32_e32 v240, 16, v7
	v_pk_mul_f32 v[228:229], v[100:101], v[228:229]
	v_pk_mul_f32 v[230:231], v[100:101], v[230:231]
	v_and_b32_e32 v235, 0xffff0000, v9
	v_lshlrev_b32_e32 v234, 16, v9
	v_pk_mul_f32 v[236:237], v[100:101], v[236:237]
	v_and_b32_e32 v239, 0xffff0000, v10
	v_lshlrev_b32_e32 v238, 16, v10
	v_pk_mul_f32 v[240:241], v[100:101], v[240:241]
	v_and_b32_e32 v243, 0xffff0000, v11
	v_lshlrev_b32_e32 v242, 16, v11
	global_load_dwordx4 v[4:7], v86, s[38:39]
	global_load_dwordx4 v[8:11], v86, s[54:55]
	v_pk_mul_f32 v[234:235], v[102:103], v[234:235]
	v_pk_mul_f32 v[238:239], v[102:103], v[238:239]
	v_pk_mul_f32 v[242:243], v[102:103], v[242:243]
	v_cvt_pk_bf16_f32 v228, v228, v229
	v_cvt_pk_bf16_f32 v229, v230, v231
	v_cvt_pk_bf16_f32 v230, v236, v237
	v_cvt_pk_bf16_f32 v231, v240, v241
	ds_write_b128 v178, v[228:231]
	v_cvt_pk_bf16_f32 v228, v232, v233
	v_cvt_pk_bf16_f32 v229, v234, v235
	v_cvt_pk_bf16_f32 v230, v238, v239
	v_cvt_pk_bf16_f32 v231, v242, v243
	ds_write_b128 v179, v[228:231]
	s_waitcnt vmcnt(7)
; #define LAS __attribute__((address_space(3)))
; __device__ __forceinline__ float bf2f(bf16_t v) { return __uint_as_float((unsigned)v << 16); }
; __device__ __forceinline__ u32x4 pack8(const float* v) { u32x4 w; w.x = cvt_pk_bf16(v[0], v[1]); w.y = cvt_pk_bf16(v[2], v[3]); w.z = cvt_pk_bf16(v[4], v[5]); w.w = cvt_pk_bf16(v[6], v[7]); return w; }
; template <int DK, int DVS, bool RET> ...
;     ...
;                 for (int j = 0; j < 4; ++j) { const int it = tid + 512 * j, p = it & 63, k0 = (it >> 6) * 8; const float bb = (float)(p + 1) * lg;
;                     const float eq = __expf(bb), ek = __expf(-bb); float a[8], c[8];
; #pragma unroll
;                     for (int e = 0; e < 8; ++e) { a[e] = bf2f((bf16_t)qv[j][e]) * eq; c[e] = bf2f((bf16_t)kv[j][e]) * ek; }
;                     *(LAS u32x4*)(QD + p * LK + k0) = pack8(a); *(LAS u32x4*)(KD + p * LK + k0) = pack8(c); }
;     ...
;             if (pg == 0) EL[kx] = __expf(bl);
;             { const int p = tid >> 3, vg = tid & 7; *(LAS vvec_t*)(VI + p * LV + vg * VPT) = vraw; }
;         }
;         if (step + 1 < 68) GLA_LOAD(step + 1);
	v_and_b32_e32 v231, 0xffff0000, v16
	v_lshlrev_b32_e32 v230, 16, v16
	v_and_b32_e32 v229, 0xffff0000, v12
	v_lshlrev_b32_e32 v228, 16, v12
	v_pk_mul_f32 v[232:233], v[102:103], v[230:231]
	v_and_b32_e32 v231, 0xffff0000, v13
	v_lshlrev_b32_e32 v230, 16, v13
	v_and_b32_e32 v237, 0xffff0000, v14
	v_lshlrev_b32_e32 v236, 16, v14
	v_and_b32_e32 v241, 0xffff0000, v15
	v_lshlrev_b32_e32 v240, 16, v15
	v_pk_mul_f32 v[228:229], v[100:101], v[228:229]
	v_pk_mul_f32 v[230:231], v[100:101], v[230:231]
	v_and_b32_e32 v235, 0xffff0000, v17
	v_lshlrev_b32_e32 v234, 16, v17
	v_pk_mul_f32 v[236:237], v[100:101], v[236:237]
	v_and_b32_e32 v239, 0xffff0000, v18
	v_lshlrev_b32_e32 v238, 16, v18
	v_pk_mul_f32 v[240:241], v[100:101], v[240:241]
	v_and_b32_e32 v243, 0xffff0000, v19
	v_lshlrev_b32_e32 v242, 16, v19
	global_load_dwordx4 v[12:15], v88, s[38:39]
	global_load_dwordx4 v[16:19], v88, s[54:55]
	v_pk_mul_f32 v[234:235], v[102:103], v[234:235]
	v_pk_mul_f32 v[238:239], v[102:103], v[238:239]
	v_pk_mul_f32 v[242:243], v[102:103], v[242:243]
	v_cvt_pk_bf16_f32 v228, v228, v229
	v_cvt_pk_bf16_f32 v229, v230, v231
	v_cvt_pk_bf16_f32 v230, v236, v237
	v_cvt_pk_bf16_f32 v231, v240, v241
	ds_write_b128 v180, v[228:231]
	v_cvt_pk_bf16_f32 v228, v232, v233
	v_cvt_pk_bf16_f32 v229, v234, v235
	v_cvt_pk_bf16_f32 v230, v238, v239
	v_cvt_pk_bf16_f32 v231, v242, v243
	ds_write_b128 v181, v[228:231]
	s_waitcnt vmcnt(7)
	v_and_b32_e32 v231, 0xffff0000, v24
	v_lshlrev_b32_e32 v230, 16, v24
	v_and_b32_e32 v229, 0xffff0000, v20
	v_lshlrev_b32_e32 v228, 16, v20
	v_pk_mul_f32 v[232:233], v[102:103], v[230:231]
	v_and_b32_e32 v231, 0xffff0000, v21
	v_lshlrev_b32_e32 v230, 16, v21
	v_and_b32_e32 v237, 0xffff0000, v22
	v_lshlrev_b32_e32 v236, 16, v22
	v_and_b32_e32 v241, 0xffff0000, v23
	v_lshlrev_b32_e32 v240, 16, v23
	v_pk_mul_f32 v[228:229], v[100:101], v[228:229]
	v_pk_mul_f32 v[230:231], v[100:101], v[230:231]
	v_and_b32_e32 v235, 0xffff0000, v25
	v_lshlrev_b32_e32 v234, 16, v25
	v_pk_mul_f32 v[236:237], v[100:101], v[236:237]
	v_and_b32_e32 v239, 0xffff0000, v26
	v_lshlrev_b32_e32 v238, 16, v26
	v_pk_mul_f32 v[240:241], v[100:101], v[240:241]
	v_and_b32_e32 v243, 0xffff0000, v27
	v_lshlrev_b32_e32 v242, 16, v27
	global_load_dwordx4 v[20:23], v90, s[38:39]
	global_load_dwordx4 v[24:27], v90, s[54:55]
	v_pk_mul_f32 v[234:235], v[102:103], v[234:235]
	v_pk_mul_f32 v[238:239], v[102:103], v[238:239]
	v_pk_mul_f32 v[242:243], v[102:103], v[242:243]
	v_cvt_pk_bf16_f32 v228, v228, v229
	v_cvt_pk_bf16_f32 v229, v230, v231
	v_cvt_pk_bf16_f32 v230, v236, v237
	v_cvt_pk_bf16_f32 v231, v240, v241
	ds_write_b128 v182, v[228:231]
	v_cvt_pk_bf16_f32 v228, v232, v233
	v_cvt_pk_bf16_f32 v229, v234, v235
	v_cvt_pk_bf16_f32 v230, v238, v239
	v_cvt_pk_bf16_f32 v231, v242, v243
	ds_write_b128 v183, v[228:231]
	s_waitcnt vmcnt(7)
	v_and_b32_e32 v231, 0xffff0000, v32
	v_lshlrev_b32_e32 v230, 16, v32
	v_and_b32_e32 v229, 0xffff0000, v28
	v_lshlrev_b32_e32 v228, 16, v28
	v_pk_mul_f32 v[232:233], v[102:103], v[230:231]
	v_and_b32_e32 v231, 0xffff0000, v29
	v_lshlrev_b32_e32 v230, 16, v29
	v_and_b32_e32 v237, 0xffff0000, v30
	v_lshlrev_b32_e32 v236, 16, v30
	v_and_b32_e32 v241, 0xffff0000, v31
	v_lshlrev_b32_e32 v240, 16, v31
	v_pk_mul_f32 v[228:229], v[100:101], v[228:229]
	v_pk_mul_f32 v[230:231], v[100:101], v[230:231]
	v_and_b32_e32 v235, 0xffff0000, v33
	v_lshlrev_b32_e32 v234, 16, v33
	v_pk_mul_f32 v[236:237], v[100:101], v[236:237]
	v_and_b32_e32 v239, 0xffff0000, v34
	v_lshlrev_b32_e32 v238, 16, v34
	v_pk_mul_f32 v[240:241], v[100:101], v[240:241]
	v_and_b32_e32 v243, 0xffff0000, v35
	v_lshlrev_b32_e32 v242, 16, v35
	global_load_dwordx4 v[28:31], v92, s[38:39]
	global_load_dwordx4 v[32:35], v92, s[54:55]
	v_pk_mul_f32 v[234:235], v[102:103], v[234:235]
	v_pk_mul_f32 v[238:239], v[102:103], v[238:239]
	v_pk_mul_f32 v[242:243], v[102:103], v[242:243]
	v_cvt_pk_bf16_f32 v228, v228, v229
	v_cvt_pk_bf16_f32 v229, v230, v231
	v_cvt_pk_bf16_f32 v230, v236, v237
	v_cvt_pk_bf16_f32 v231, v240, v241
	ds_write_b128 v184, v[228:231]
	v_cvt_pk_bf16_f32 v228, v232, v233
	v_cvt_pk_bf16_f32 v229, v234, v235
	v_cvt_pk_bf16_f32 v230, v238, v239
	v_cvt_pk_bf16_f32 v231, v242, v243
	ds_write_b128 v185, v[228:231]
	s_and_saveexec_b64 s[40:41], vcc
	ds_write_b32 v171, v173
	s_or_b64 exec, exec, s[40:41]
	s_add_i32 s36, s45, 1
	s_cmpk_eq_i32 s42, 0xffbd
	s_waitcnt vmcnt(8)
	ds_write_b128 v172, v[212:215]
	s_branch .LBB0_70
